# P1 row-norm pass: the once-read x stream loaded non-temporal
# speedup vs baseline: 1.0206x; 1.0206x over previous
; __device__ __forceinline__ void p_hrows(const float* X, bf16* H, const float* ng, const float* mod, int gw, int NGW, int lane) {
;     ...
;         for (int r0 = 0; r0 < 16; r0 += 4) {
;             f32x4 v[4][4];
; #pragma unroll
;             for (int rr = 0; rr < 4; ++rr) { const float* xr = X + (size_t)(m0 + r0 + rr) * D;
; #pragma unroll
;                 for (int j = 0; j < 4; ++j) v[rr][j] = *(const f32x4*)(xr + 4 * lane + 256 * j); }
; #pragma unroll
;             for (int rr = 0; rr < 4; ++rr) {
;                 float ss = 0.f;
; #pragma unroll
;                 for (int j = 0; j < 4; ++j) ss += (v[rr][j].x * v[rr][j].x + v[rr][j].y * v[rr][j].y) + (v[rr][j].z * v[rr][j].z + v[rr][j].w * v[rr][j].w);
;                 ss = wave_sum(ss); const float rstd = 1.0f / sqrtf(ss * (1.f / D) + EPS);
.LBB0_136:
	v_lshl_add_u64 v[16:17], s[34:35], 0, v[82:83]
	v_lshl_add_u64 v[18:19], s[40:41], 0, v[82:83]
	v_lshl_add_u64 v[20:21], s[46:47], 0, v[82:83]
	v_lshl_add_u64 v[106:107], s[38:39], 0, v[82:83]
	global_load_dwordx4 v[76:79], v[16:17], off nt
	global_load_dwordx4 v[68:71], v[16:17], off offset:1024 nt
	global_load_dwordx4 v[64:67], v[16:17], off offset:3072 nt
	global_load_dwordx4 v[72:75], v[16:17], off offset:2048 nt
	global_load_dwordx4 v[60:63], v[18:19], off nt
	global_load_dwordx4 v[56:59], v[18:19], off offset:1024 nt
	global_load_dwordx4 v[52:55], v[18:19], off offset:2048 nt
	global_load_dwordx4 v[48:51], v[18:19], off offset:3072 nt
	global_load_dwordx4 v[44:47], v[20:21], off nt
	global_load_dwordx4 v[40:43], v[20:21], off offset:1024 nt
	global_load_dwordx4 v[36:39], v[20:21], off offset:2048 nt
	global_load_dwordx4 v[32:35], v[20:21], off offset:3072 nt
	global_load_dwordx4 v[28:31], v[106:107], off nt
	global_load_dwordx4 v[24:27], v[106:107], off offset:1024 nt
	s_nop 0
	global_load_dwordx4 v[20:23], v[106:107], off offset:2048 nt
	global_load_dwordx4 v[16:19], v[106:107], off offset:3072 nt
	v_lshl_add_u64 v[104:105], s[30:31], 0, v[86:87]
	v_add_co_u32_e32 v110, vcc, s54, v104
	v_lshl_add_u64 v[108:109], s[36:37], 0, v[86:87]
	s_nop 0
	v_addc_co_u32_e32 v111, vcc, 0, v105, vcc
	v_add_co_u32_e32 v108, vcc, s54, v108
	v_lshl_add_u64 v[120:121], s[42:43], 0, v[86:87]
	s_nop 0
	v_addc_co_u32_e32 v109, vcc, 0, v109, vcc
	v_add_co_u32_e32 v106, vcc, s54, v120
	v_lshl_add_u64 v[122:123], s[44:45], 0, v[86:87]
	s_nop 0
	v_addc_co_u32_e32 v107, vcc, 0, v121, vcc
	v_add_co_u32_e32 v104, vcc, s54, v122
	s_add_u32 s30, s30, 0x2000
	s_nop 0
	v_addc_co_u32_e32 v105, vcc, 0, v123, vcc
	s_addc_u32 s31, s31, 0
	s_add_i32 s21, s21, 4
	s_add_u32 s34, s34, 0x4000
	s_addc_u32 s35, s35, 0
	s_add_u32 s36, s36, 0x2000
	s_addc_u32 s37, s37, 0
	s_add_u32 s38, s38, 0x4000
	s_addc_u32 s39, s39, 0
	s_add_u32 s40, s40, 0x4000
	s_addc_u32 s41, s41, 0
	s_add_u32 s42, s42, 0x2000
	s_addc_u32 s43, s43, 0
	s_add_u32 s44, s44, 0x2000
	s_addc_u32 s45, s45, 0
	s_add_u32 s46, s46, 0x4000
	s_addc_u32 s47, s47, 0
	s_cmp_gt_u32 s21, 11
	s_waitcnt vmcnt(15)
	v_pk_mul_f32 v[120:121], v[78:79], v[78:79]
	v_pk_mul_f32 v[122:123], v[76:77], v[76:77]
	s_waitcnt vmcnt(14)
	v_pk_mul_f32 v[124:125], v[70:71], v[70:71]
	v_pk_mul_f32 v[126:127], v[68:69], v[68:69]
	s_waitcnt vmcnt(12)
	v_mul_f32_e32 v128, v73, v73
	v_mul_f32_e32 v130, v75, v75
	s_waitcnt vmcnt(11)
	v_pk_mul_f32 v[132:133], v[62:63], v[62:63]
	v_pk_mul_f32 v[134:135], v[60:61], v[60:61]
	s_waitcnt vmcnt(10)
	v_pk_mul_f32 v[136:137], v[58:59], v[58:59]
	v_pk_mul_f32 v[138:139], v[56:57], v[56:57]
	s_waitcnt vmcnt(9)
	v_mul_f32_e32 v140, v53, v53
	v_mul_f32_e32 v142, v55, v55
	s_waitcnt vmcnt(7)
	v_pk_mul_f32 v[144:145], v[46:47], v[46:47]
	v_pk_mul_f32 v[146:147], v[44:45], v[44:45]
	s_waitcnt vmcnt(6)
	v_pk_mul_f32 v[148:149], v[42:43], v[42:43]
	v_pk_mul_f32 v[150:151], v[40:41], v[40:41]
	v_pk_mov_b32 v[168:169], v[122:123], v[120:121] op_sel:[1,0]
	v_mov_b32_e32 v123, v121
	v_pk_mov_b32 v[120:121], v[126:127], v[124:125] op_sel:[1,0]
	v_mov_b32_e32 v127, v125
	s_waitcnt vmcnt(5)
	v_mul_f32_e32 v152, v37, v37
	v_mul_f32_e32 v154, v39, v39
	s_waitcnt vmcnt(3)
	v_pk_mul_f32 v[156:157], v[30:31], v[30:31]
	v_pk_mul_f32 v[158:159], v[28:29], v[28:29]
	s_waitcnt vmcnt(2)
	v_pk_mul_f32 v[160:161], v[26:27], v[26:27]
	v_pk_mul_f32 v[162:163], v[24:25], v[24:25]
	v_pk_fma_f32 v[124:125], v[72:73], v[72:73], v[128:129] op_sel_hi:[1,1,0]
	v_pk_fma_f32 v[128:129], v[74:75], v[74:75], v[130:131] op_sel_hi:[1,1,0]
	v_pk_mov_b32 v[130:131], v[134:135], v[132:133] op_sel:[1,0]
	v_mov_b32_e32 v135, v133
	v_pk_mov_b32 v[132:133], v[138:139], v[136:137] op_sel:[1,0]
	v_mov_b32_e32 v139, v137
	v_pk_fma_f32 v[136:137], v[52:53], v[52:53], v[140:141] op_sel_hi:[1,1,0]
	v_pk_fma_f32 v[140:141], v[54:55], v[54:55], v[142:143] op_sel_hi:[1,1,0]
	v_pk_mov_b32 v[142:143], v[146:147], v[144:145] op_sel:[1,0]
	v_mov_b32_e32 v147, v145
	v_pk_mov_b32 v[144:145], v[150:151], v[148:149] op_sel:[1,0]
	v_mov_b32_e32 v151, v149
	v_pk_add_f32 v[122:123], v[168:169], v[122:123]
	v_pk_add_f32 v[120:121], v[120:121], v[126:127]
	v_mul_f32_e32 v167, v66, v66
	v_mul_f32_e32 v170, v67, v67
	v_mul_f32_e32 v171, v64, v64
	v_mul_f32_e32 v172, v65, v65
	v_pk_fma_f32 v[148:149], v[36:37], v[36:37], v[152:153] op_sel_hi:[1,1,0]
	v_pk_fma_f32 v[152:153], v[38:39], v[38:39], v[154:155] op_sel_hi:[1,1,0]
	v_pk_mov_b32 v[154:155], v[158:159], v[156:157] op_sel:[1,0]
	v_mov_b32_e32 v159, v157
	v_pk_mov_b32 v[156:157], v[162:163], v[160:161] op_sel:[1,0]
	v_mov_b32_e32 v163, v161
	v_pk_add_f32 v[126:127], v[130:131], v[134:135]
	v_pk_add_f32 v[130:131], v[132:133], v[138:139]
	v_pk_add_f32 v[132:133], v[142:143], v[146:147]
	v_pk_add_f32 v[134:135], v[144:145], v[150:151]
	v_pk_add_f32 v[122:123], v[122:123], v[122:123] op_sel:[0,1] op_sel_hi:[1,0]
	v_pk_add_f32 v[120:121], v[120:121], v[120:121] op_sel:[0,1] op_sel_hi:[1,0]
	v_mul_f32_e32 v173, v50, v50
	v_mul_f32_e32 v174, v51, v51
	v_mul_f32_e32 v175, v48, v48
	v_mul_f32_e32 v176, v49, v49
	v_mul_f32_e32 v177, v34, v34
	v_mul_f32_e32 v178, v35, v35
	v_mul_f32_e32 v179, v32, v32
	v_mul_f32_e32 v180, v33, v33
	s_waitcnt vmcnt(1)
	v_mul_f32_e32 v164, v21, v21
	v_mul_f32_e32 v166, v23, v23
	v_mov_b32_e32 v125, v167
	v_mov_b32_e32 v129, v170
	v_pk_add_f32 v[138:139], v[154:155], v[158:159]
	v_pk_add_f32 v[142:143], v[156:157], v[162:163]
	v_pk_add_f32 v[126:127], v[126:127], v[126:127] op_sel:[0,1] op_sel_hi:[1,0]
	v_pk_add_f32 v[130:131], v[130:131], v[130:131] op_sel:[0,1] op_sel_hi:[1,0]
	v_pk_add_f32 v[132:133], v[132:133], v[132:133] op_sel:[0,1] op_sel_hi:[1,0]
	v_pk_add_f32 v[134:135], v[134:135], v[134:135] op_sel:[0,1] op_sel_hi:[1,0]
	v_mov_b32_e32 v123, v171
	v_mov_b32_e32 v121, v172
	s_waitcnt vmcnt(0)
; __device__ __forceinline__ float wave_sum(float v) {
; #pragma unroll
;     for (int o = 1; o < 64; o <<= 1) v += __shfl_xor(v, o);
;     return v;
; }
; __device__ __forceinline__ void p_hrows(const float* X, bf16* H, const float* ng, const float* mod, int gw, int NGW, int lane) {
;     ...
;             for (int rr = 0; rr < 4; ++rr) {
;                 float ss = 0.f;
; #pragma unroll
;                 for (int j = 0; j < 4; ++j) ss += (v[rr][j].x * v[rr][j].x + v[rr][j].y * v[rr][j].y) + (v[rr][j].z * v[rr][j].z + v[rr][j].w * v[rr][j].w);
;                 ss = wave_sum(ss); const float rstd = 1.0f / sqrtf(ss * (1.f / D) + EPS);
	v_mul_f32_e32 v181, v18, v18
	v_mul_f32_e32 v182, v19, v19
	v_mul_f32_e32 v183, v16, v16
	v_mul_f32_e32 v184, v17, v17
	v_pk_fma_f32 v[160:161], v[20:21], v[20:21], v[164:165] op_sel_hi:[1,1,0]
	v_pk_fma_f32 v[164:165], v[22:23], v[22:23], v[166:167] op_sel_hi:[1,1,0]
	v_mov_b32_e32 v137, v173
	v_mov_b32_e32 v141, v174
	v_mov_b32_e32 v149, v177
	v_mov_b32_e32 v153, v178
	v_pk_add_f32 v[124:125], v[124:125], v[128:129]
	v_pk_add_f32 v[138:139], v[138:139], v[138:139] op_sel:[0,1] op_sel_hi:[1,0]
	v_pk_add_f32 v[142:143], v[142:143], v[142:143] op_sel:[0,1] op_sel_hi:[1,0]
	v_mov_b32_e32 v127, v175
	v_mov_b32_e32 v131, v176
	v_mov_b32_e32 v133, v179
	v_mov_b32_e32 v135, v180
	v_pk_add_f32 v[120:121], v[122:123], v[120:121]
	v_mov_b32_e32 v161, v181
	v_mov_b32_e32 v165, v182
	v_pk_add_f32 v[128:129], v[136:137], v[140:141]
	v_pk_add_f32 v[136:137], v[148:149], v[152:153]
	v_mov_b32_e32 v139, v183
	v_mov_b32_e32 v143, v184
	v_pk_add_f32 v[122:123], v[126:127], v[130:131]
	v_pk_add_f32 v[126:127], v[132:133], v[134:135]
	v_pk_add_f32 v[120:121], v[120:121], v[124:125]
	v_pk_add_f32 v[140:141], v[160:161], v[164:165]
	v_pk_add_f32 v[130:131], v[138:139], v[142:143]
	v_pk_add_f32 v[122:123], v[122:123], v[128:129]
	v_pk_add_f32 v[124:125], v[126:127], v[136:137]
	v_add_f32_e32 v120, v120, v121
	v_pk_add_f32 v[126:127], v[130:131], v[140:141]
	v_add_f32_e32 v121, v122, v123
	v_add_f32_e32 v122, v124, v125
	ds_bpermute_b32 v124, v112, v120
	v_add_f32_e32 v123, v126, v127
	ds_bpermute_b32 v125, v112, v121
	ds_bpermute_b32 v126, v112, v122
	ds_bpermute_b32 v127, v112, v123
	s_waitcnt lgkmcnt(3)
	v_add_f32_e32 v120, v120, v124
	ds_bpermute_b32 v124, v113, v120
	s_waitcnt lgkmcnt(3)
	v_add_f32_e32 v121, v121, v125
	s_waitcnt lgkmcnt(2)
	v_add_f32_e32 v122, v122, v126
	ds_bpermute_b32 v125, v113, v121
	ds_bpermute_b32 v126, v113, v122
	s_waitcnt lgkmcnt(3)
	v_add_f32_e32 v123, v123, v127
	ds_bpermute_b32 v127, v113, v123
	s_waitcnt lgkmcnt(3)
	v_add_f32_e32 v120, v120, v124
	s_waitcnt lgkmcnt(2)
	v_add_f32_e32 v121, v121, v125
	s_waitcnt lgkmcnt(1)
	v_add_f32_e32 v122, v122, v126
	ds_bpermute_b32 v124, v114, v120
	ds_bpermute_b32 v125, v114, v121
	ds_bpermute_b32 v126, v114, v122
	s_waitcnt lgkmcnt(3)
	v_add_f32_e32 v123, v123, v127
	ds_bpermute_b32 v127, v114, v123
	s_waitcnt lgkmcnt(3)
	v_add_f32_e32 v120, v120, v124
	s_waitcnt lgkmcnt(2)
	v_add_f32_e32 v121, v121, v125
	s_waitcnt lgkmcnt(1)
	v_add_f32_e32 v122, v122, v126
	ds_bpermute_b32 v124, v115, v120
	ds_bpermute_b32 v125, v115, v121
	ds_bpermute_b32 v126, v115, v122
	s_waitcnt lgkmcnt(3)
	v_add_f32_e32 v123, v123, v127
	ds_bpermute_b32 v127, v115, v123
	s_waitcnt lgkmcnt(3)
	v_add_f32_e32 v120, v120, v124
	s_waitcnt lgkmcnt(2)
	v_add_f32_e32 v121, v121, v125
	s_waitcnt lgkmcnt(1)
	v_add_f32_e32 v122, v122, v126
	ds_bpermute_b32 v124, v116, v120
	ds_bpermute_b32 v125, v116, v121
	ds_bpermute_b32 v126, v116, v122
	s_waitcnt lgkmcnt(3)
	v_add_f32_e32 v123, v123, v127
	ds_bpermute_b32 v127, v116, v123
	s_waitcnt lgkmcnt(3)
	v_add_f32_e32 v120, v120, v124
	s_waitcnt lgkmcnt(2)
	v_add_f32_e32 v121, v121, v125
	s_waitcnt lgkmcnt(1)
	v_add_f32_e32 v122, v122, v126
	ds_bpermute_b32 v124, v117, v120
	ds_bpermute_b32 v125, v117, v121
	ds_bpermute_b32 v126, v117, v122
	s_waitcnt lgkmcnt(3)
	v_add_f32_e32 v123, v123, v127
	ds_bpermute_b32 v127, v117, v123
	s_waitcnt lgkmcnt(3)
	v_add_f32_e32 v120, v120, v124
	s_waitcnt lgkmcnt(2)
	v_add_f32_e32 v121, v121, v125
	s_waitcnt lgkmcnt(1)
	v_add_f32_e32 v122, v122, v126
	v_fmamk_f32 v120, v120, 0x3a800000, v118
	v_fmamk_f32 v121, v121, 0x3a800000, v118
	v_fmamk_f32 v122, v122, 0x3a800000, v118
	v_mul_f32_e32 v124, 0x4f800000, v120
	v_cmp_gt_f32_e64 s[8:9], s53, v120
	s_waitcnt lgkmcnt(0)
	v_add_f32_e32 v123, v123, v127
	v_mul_f32_e32 v125, 0x4f800000, v121
	v_cmp_gt_f32_e32 vcc, s53, v121
	v_mul_f32_e32 v126, 0x4f800000, v122
	v_cmp_gt_f32_e64 s[2:3], s53, v122
	v_cndmask_b32_e64 v120, v120, v124, s[8:9]
	v_fmamk_f32 v123, v123, 0x3a800000, v118
	v_cndmask_b32_e32 v121, v121, v125, vcc
	v_cndmask_b32_e64 v122, v122, v126, s[2:3]
	v_sqrt_f32_e32 v124, v120
	v_mul_f32_e32 v127, 0x4f800000, v123
	v_cmp_gt_f32_e64 s[6:7], s53, v123
	v_sqrt_f32_e32 v125, v121
	v_sqrt_f32_e32 v126, v122
	v_cndmask_b32_e64 v123, v123, v127, s[6:7]
	v_sqrt_f32_e32 v127, v123
	v_add_u32_e32 v128, -1, v124
	v_add_u32_e32 v129, 1, v124
	v_add_u32_e32 v130, -1, v125
	v_add_u32_e32 v132, -1, v126
	v_fma_f32 v136, -v128, v124, v120
	v_add_u32_e32 v131, 1, v125
	v_add_u32_e32 v133, 1, v126
	v_fma_f32 v137, -v129, v124, v120
	v_fma_f32 v138, -v130, v125, v121
	v_fma_f32 v140, -v132, v126, v122
	v_cmp_ge_f32_e64 s[10:11], 0, v136
	v_add_u32_e32 v134, -1, v127
	v_fma_f32 v139, -v131, v125, v121
	v_fma_f32 v141, -v133, v126, v122
	v_cndmask_b32_e64 v124, v124, v128, s[10:11]
	v_cmp_ge_f32_e64 s[10:11], 0, v138
	v_cmp_ge_f32_e64 s[12:13], 0, v140
	v_cmp_lt_f32_e64 s[16:17], 0, v137
	v_add_u32_e32 v135, 1, v127
	v_fma_f32 v142, -v134, v127, v123
	v_cndmask_b32_e64 v125, v125, v130, s[10:11]
	v_cmp_lt_f32_e64 s[10:11], 0, v139
	v_cndmask_b32_e64 v126, v126, v132, s[12:13]
	v_cmp_lt_f32_e64 s[12:13], 0, v141
	v_cndmask_b32_e64 v124, v124, v129, s[16:17]
	v_fma_f32 v143, -v135, v127, v123
	v_cmp_ge_f32_e64 s[14:15], 0, v142
	v_cndmask_b32_e64 v125, v125, v131, s[10:11]
	v_cndmask_b32_e64 v126, v126, v133, s[12:13]
	v_mul_f32_e32 v128, 0x37800000, v124
	v_cndmask_b32_e64 v127, v127, v134, s[14:15]
	v_cmp_lt_f32_e64 s[14:15], 0, v143
	v_mul_f32_e32 v129, 0x37800000, v125
	v_mul_f32_e32 v130, 0x37800000, v126
	v_cndmask_b32_e64 v124, v124, v128, s[8:9]
	v_cmp_class_f32_e64 s[8:9], v120, v119
; __device__ __forceinline__ unsigned cvtpk(float lo, float hi) { f32x2_t v = {lo, hi}; bf16x2_t b = __builtin_convertvector(v, bf16x2_t); return __builtin_bit_cast(unsigned, b); }
; __device__ __forceinline__ void p_hrows(const float* X, bf16* H, const float* ng, const float* mod, int gw, int NGW, int lane) {
;     ...
;                 ss = wave_sum(ss); const float rstd = 1.0f / sqrtf(ss * (1.f / D) + EPS);
;                 bf16* hr = H + (size_t)(m0 + r0 + rr) * D;
; #pragma unroll
;                 for (int j = 0; j < 4; ++j) { const f32x4 o = v[rr][j] * rstd * A[j] + SH[j]; u32x2 w; w.x = cvtpk(o.x, o.y); w.y = cvtpk(o.z, o.w); *(u32x2*)(hr + 4 * lane + 256 * j) = w; }
	v_cndmask_b32_e64 v127, v127, v135, s[14:15]
	v_cndmask_b32_e32 v125, v125, v129, vcc
	v_cmp_class_f32_e32 vcc, v121, v119
	v_cndmask_b32_e64 v126, v126, v130, s[2:3]
	v_cmp_class_f32_e64 s[2:3], v122, v119
	v_cndmask_b32_e64 v120, v124, v120, s[8:9]
	v_mul_f32_e32 v131, 0x37800000, v127
	v_cndmask_b32_e32 v121, v125, v121, vcc
	v_cndmask_b32_e64 v122, v126, v122, s[2:3]
	v_div_scale_f32 v124, s[2:3], v120, v120, 1.0
	v_cndmask_b32_e64 v127, v127, v131, s[6:7]
	v_cmp_class_f32_e64 s[6:7], v123, v119
	v_div_scale_f32 v126, s[2:3], v121, v121, 1.0
	v_rcp_f32_e32 v132, v124
	v_cndmask_b32_e64 v123, v127, v123, s[6:7]
	v_div_scale_f32 v128, s[6:7], v122, v122, 1.0
	v_rcp_f32_e32 v133, v126
	v_div_scale_f32 v130, s[8:9], v123, v123, 1.0
	v_rcp_f32_e32 v134, v128
	v_rcp_f32_e32 v135, v130
	v_fma_f32 v136, -v124, v132, 1.0
	v_div_scale_f32 v125, vcc, 1.0, v120, 1.0
	v_fma_f32 v137, -v126, v133, 1.0
	v_fmac_f32_e32 v132, v136, v132
	v_div_scale_f32 v127, s[2:3], 1.0, v121, 1.0
	v_fma_f32 v138, -v128, v134, 1.0
	v_fmac_f32_e32 v133, v137, v133
	v_mul_f32_e32 v136, v125, v132
	v_div_scale_f32 v129, s[6:7], 1.0, v122, 1.0
	v_fma_f32 v139, -v130, v135, 1.0
	v_fmac_f32_e32 v134, v138, v134
	v_mul_f32_e32 v137, v127, v133
	v_fma_f32 v140, -v124, v136, v125
	v_div_scale_f32 v131, s[8:9], 1.0, v123, 1.0
	v_fmac_f32_e32 v135, v139, v135
	v_mul_f32_e32 v138, v129, v134
	v_fma_f32 v141, -v126, v137, v127
	v_fmac_f32_e32 v136, v140, v132
	v_mul_f32_e32 v139, v131, v135
	v_fma_f32 v142, -v128, v138, v129
	v_fmac_f32_e32 v137, v141, v133
	v_fma_f32 v124, -v124, v136, v125
	v_fma_f32 v143, -v130, v139, v131
	v_fmac_f32_e32 v138, v142, v134
	v_fma_f32 v125, -v126, v137, v127
	v_div_fmas_f32 v124, v124, v132, v136
	s_mov_b64 vcc, s[2:3]
	v_fmac_f32_e32 v139, v143, v135
	v_fma_f32 v126, -v128, v138, v129
	v_div_fixup_f32 v120, v124, v120, 1.0
	v_div_fmas_f32 v124, v125, v133, v137
	s_mov_b64 vcc, s[6:7]
	v_fma_f32 v127, -v130, v139, v131
	v_pk_mul_f32 v[76:77], v[76:77], v[120:121] op_sel_hi:[1,0]
	v_pk_mul_f32 v[78:79], v[78:79], v[120:121] op_sel_hi:[1,0]
	v_pk_mul_f32 v[68:69], v[68:69], v[120:121] op_sel_hi:[1,0]
	v_pk_mul_f32 v[70:71], v[70:71], v[120:121] op_sel_hi:[1,0]
	v_pk_mul_f32 v[72:73], v[72:73], v[120:121] op_sel_hi:[1,0]
	v_pk_mul_f32 v[74:75], v[74:75], v[120:121] op_sel_hi:[1,0]
	v_pk_mul_f32 v[64:65], v[64:65], v[120:121] op_sel_hi:[1,0]
	v_pk_mul_f32 v[66:67], v[66:67], v[120:121] op_sel_hi:[1,0]
	v_div_fixup_f32 v120, v124, v121, 1.0
	v_div_fmas_f32 v121, v126, v134, v138
	s_mov_b64 vcc, s[8:9]
	v_pk_mul_f32 v[60:61], v[60:61], v[120:121] op_sel_hi:[1,0]
	v_pk_mul_f32 v[62:63], v[62:63], v[120:121] op_sel_hi:[1,0]
	v_pk_mul_f32 v[56:57], v[56:57], v[120:121] op_sel_hi:[1,0]
	v_pk_mul_f32 v[58:59], v[58:59], v[120:121] op_sel_hi:[1,0]
	v_pk_mul_f32 v[52:53], v[52:53], v[120:121] op_sel_hi:[1,0]
	v_pk_mul_f32 v[54:55], v[54:55], v[120:121] op_sel_hi:[1,0]
	v_pk_mul_f32 v[48:49], v[48:49], v[120:121] op_sel_hi:[1,0]
	v_pk_mul_f32 v[50:51], v[50:51], v[120:121] op_sel_hi:[1,0]
	v_div_fixup_f32 v120, v121, v122, 1.0
	v_pk_fma_f32 v[66:67], v[100:101], v[66:67], v[14:15]
	v_pk_fma_f32 v[64:65], v[102:103], v[64:65], v[12:13]
	v_div_fmas_f32 v121, v127, v135, v139
	v_cvt_pk_bf16_f32 v64, v64, v65
	v_cvt_pk_bf16_f32 v65, v66, v67
	v_div_fixup_f32 v66, v121, v123, 1.0
	v_pk_mul_f32 v[44:45], v[44:45], v[120:121] op_sel_hi:[1,0]
	v_pk_mul_f32 v[46:47], v[46:47], v[120:121] op_sel_hi:[1,0]
	v_pk_mul_f32 v[28:29], v[28:29], v[66:67] op_sel_hi:[1,0]
	v_pk_mul_f32 v[30:31], v[30:31], v[66:67] op_sel_hi:[1,0]
	v_pk_fma_f32 v[78:79], v[88:89], v[78:79], v[2:3]
	v_pk_fma_f32 v[76:77], v[90:91], v[76:77], v[0:1]
	v_pk_mul_f32 v[40:41], v[40:41], v[120:121] op_sel_hi:[1,0]
	v_pk_mul_f32 v[42:43], v[42:43], v[120:121] op_sel_hi:[1,0]
	v_pk_mul_f32 v[36:37], v[36:37], v[120:121] op_sel_hi:[1,0]
	v_pk_mul_f32 v[38:39], v[38:39], v[120:121] op_sel_hi:[1,0]
	v_pk_mul_f32 v[32:33], v[32:33], v[120:121] op_sel_hi:[1,0]
; __device__ __forceinline__ unsigned cvtpk(float lo, float hi) { f32x2_t v = {lo, hi}; bf16x2_t b = __builtin_convertvector(v, bf16x2_t); return __builtin_bit_cast(unsigned, b); }
; __device__ __forceinline__ void p_hrows(const float* X, bf16* H, const float* ng, const float* mod, int gw, int NGW, int lane) {
;     ...
;             for (int rr = 0; rr < 4; ++rr) {
;                 float ss = 0.f;
; #pragma unroll
;                 for (int j = 0; j < 4; ++j) ss += (v[rr][j].x * v[rr][j].x + v[rr][j].y * v[rr][j].y) + (v[rr][j].z * v[rr][j].z + v[rr][j].w * v[rr][j].w);
;                 ss = wave_sum(ss); const float rstd = 1.0f / sqrtf(ss * (1.f / D) + EPS);
;                 bf16* hr = H + (size_t)(m0 + r0 + rr) * D;
; #pragma unroll
;                 for (int j = 0; j < 4; ++j) { const f32x4 o = v[rr][j] * rstd * A[j] + SH[j]; u32x2 w; w.x = cvtpk(o.x, o.y); w.y = cvtpk(o.z, o.w); *(u32x2*)(hr + 4 * lane + 256 * j) = w; }
;             }
	v_pk_mul_f32 v[34:35], v[34:35], v[120:121] op_sel_hi:[1,0]
	v_pk_fma_f32 v[62:63], v[88:89], v[62:63], v[2:3]
	v_pk_fma_f32 v[60:61], v[90:91], v[60:61], v[0:1]
	v_pk_mul_f32 v[24:25], v[24:25], v[66:67] op_sel_hi:[1,0]
	v_pk_mul_f32 v[26:27], v[26:27], v[66:67] op_sel_hi:[1,0]
	v_pk_mul_f32 v[20:21], v[20:21], v[66:67] op_sel_hi:[1,0]
	v_pk_mul_f32 v[22:23], v[22:23], v[66:67] op_sel_hi:[1,0]
	v_pk_mul_f32 v[16:17], v[16:17], v[66:67] op_sel_hi:[1,0]
	v_pk_mul_f32 v[18:19], v[18:19], v[66:67] op_sel_hi:[1,0]
	v_pk_fma_f32 v[46:47], v[88:89], v[46:47], v[2:3]
	v_pk_fma_f32 v[44:45], v[90:91], v[44:45], v[0:1]
	v_pk_fma_f32 v[30:31], v[88:89], v[30:31], v[2:3]
	v_pk_fma_f32 v[28:29], v[90:91], v[28:29], v[0:1]
	v_pk_fma_f32 v[70:71], v[92:93], v[70:71], v[6:7]
	v_pk_fma_f32 v[68:69], v[94:95], v[68:69], v[4:5]
	v_pk_fma_f32 v[74:75], v[96:97], v[74:75], v[10:11]
	v_pk_fma_f32 v[72:73], v[98:99], v[72:73], v[8:9]
	v_cvt_pk_bf16_f32 v76, v76, v77
	v_cvt_pk_bf16_f32 v77, v78, v79
	v_pk_fma_f32 v[58:59], v[92:93], v[58:59], v[6:7]
	v_pk_fma_f32 v[56:57], v[94:95], v[56:57], v[4:5]
	v_pk_fma_f32 v[54:55], v[96:97], v[54:55], v[10:11]
	v_pk_fma_f32 v[52:53], v[98:99], v[52:53], v[8:9]
	v_pk_fma_f32 v[50:51], v[100:101], v[50:51], v[14:15]
	v_pk_fma_f32 v[48:49], v[102:103], v[48:49], v[12:13]
	v_cvt_pk_bf16_f32 v60, v60, v61
	v_cvt_pk_bf16_f32 v61, v62, v63
	v_pk_fma_f32 v[42:43], v[92:93], v[42:43], v[6:7]
	v_pk_fma_f32 v[40:41], v[94:95], v[40:41], v[4:5]
	v_pk_fma_f32 v[38:39], v[96:97], v[38:39], v[10:11]
	v_pk_fma_f32 v[36:37], v[98:99], v[36:37], v[8:9]
	v_pk_fma_f32 v[34:35], v[100:101], v[34:35], v[14:15]
	v_pk_fma_f32 v[32:33], v[102:103], v[32:33], v[12:13]
	v_cvt_pk_bf16_f32 v44, v44, v45
	v_cvt_pk_bf16_f32 v45, v46, v47
	v_pk_fma_f32 v[26:27], v[92:93], v[26:27], v[6:7]
	v_pk_fma_f32 v[24:25], v[94:95], v[24:25], v[4:5]
	v_pk_fma_f32 v[22:23], v[96:97], v[22:23], v[10:11]
	v_pk_fma_f32 v[20:21], v[98:99], v[20:21], v[8:9]
	v_pk_fma_f32 v[18:19], v[100:101], v[18:19], v[14:15]
	v_pk_fma_f32 v[16:17], v[102:103], v[16:17], v[12:13]
	v_cvt_pk_bf16_f32 v28, v28, v29
	v_cvt_pk_bf16_f32 v29, v30, v31
	v_cvt_pk_bf16_f32 v68, v68, v69
	v_cvt_pk_bf16_f32 v69, v70, v71
	v_cvt_pk_bf16_f32 v70, v72, v73
	v_cvt_pk_bf16_f32 v71, v74, v75
	global_store_dwordx2 v[110:111], v[76:77], off
	global_store_dwordx2 v[110:111], v[68:69], off offset:512
	global_store_dwordx2 v[110:111], v[70:71], off offset:1024
	global_store_dwordx2 v[110:111], v[64:65], off offset:1536
	v_cvt_pk_bf16_f32 v56, v56, v57
	v_cvt_pk_bf16_f32 v57, v58, v59
	v_cvt_pk_bf16_f32 v52, v52, v53
	v_cvt_pk_bf16_f32 v53, v54, v55
	v_cvt_pk_bf16_f32 v48, v48, v49
	v_cvt_pk_bf16_f32 v49, v50, v51
	global_store_dwordx2 v[108:109], v[60:61], off
	global_store_dwordx2 v[108:109], v[56:57], off offset:512
	global_store_dwordx2 v[108:109], v[52:53], off offset:1024
	global_store_dwordx2 v[108:109], v[48:49], off offset:1536
	v_cvt_pk_bf16_f32 v40, v40, v41
	v_cvt_pk_bf16_f32 v41, v42, v43
	v_cvt_pk_bf16_f32 v36, v36, v37
	v_cvt_pk_bf16_f32 v37, v38, v39
	v_cvt_pk_bf16_f32 v32, v32, v33
	v_cvt_pk_bf16_f32 v33, v34, v35
	global_store_dwordx2 v[106:107], v[44:45], off
	global_store_dwordx2 v[106:107], v[40:41], off offset:512
	global_store_dwordx2 v[106:107], v[36:37], off offset:1024
	global_store_dwordx2 v[106:107], v[32:33], off offset:1536
	v_cvt_pk_bf16_f32 v24, v24, v25
	v_cvt_pk_bf16_f32 v25, v26, v27
	v_cvt_pk_bf16_f32 v20, v20, v21
	v_cvt_pk_bf16_f32 v21, v22, v23
	v_cvt_pk_bf16_f32 v16, v16, v17
	v_cvt_pk_bf16_f32 v17, v18, v19
	global_store_dwordx2 v[104:105], v[28:29], off
	global_store_dwordx2 v[104:105], v[24:25], off offset:512
	global_store_dwordx2 v[104:105], v[20:21], off offset:1024
	global_store_dwordx2 v[104:105], v[16:17], off offset:1536
	s_cbranch_scc0 .LBB0_136
	s_add_i32 s55, s55, s85
	s_add_i32 s20, s20, s51
	s_add_i32 s22, s22, s51
	s_add_i32 s24, s24, s51
	s_add_i32 s26, s26, s51
	s_cmpk_gt_i32 s55, 0x7ff
	s_mov_b64 s[0:1], s[56:57]
	s_cbranch_scc0 .LBB0_135
